# attention loop re-scheduled as [QK,PV,PV]x8 with ks-outer PV order so softmax VALU spreads over all 24 MFMA gaps (p1 half finished in the next iteration)
# baseline (speedup 1.0000x reference)
; #define ATT_WAIT_BAR(N) asm volatile("s_waitcnt vmcnt(" #N ") lgkmcnt(0)\n\ts_barrier" ::: "memory")
; #define DMA_T(t, s) do { const long go_ = (long)(t) * KVBLK * PITCH; const unsigned sd_ = (unsigned)__builtin_amdgcn_readfirstlane(pdst + (s) * SLOTB); \
;         glds16(ksrc + go_, sd_); glds16(ksrc + go_ + 64, sd_ + OFF_K1); glds16(vsrc + go_, sd_ + OFF_V); glds16(vsrc + go_ + 64, sd_ + OFF_V + 8192); } while (0)
; __device__ __forceinline__ void attn_unit(const int b, const int h, const int qb, const bf16_t* Q, const bf16_t* K, const bf16_t* V, bf16_t* O, ATT_LAS char* shm, const float lam) {
;     const int tid = threadIdx.x, lane = tid & 63, r32 = lane & 31, hi = lane >> 5; const int wid = __builtin_amdgcn_readfirstlane(tid >> 6), sub = wid >> 2, w4 = wid & 3;
;     const long rowbase = (long)b * SEQ; const int q0 = qb * QB2;
;     const bf16_t* Qw = Q + (rowbase + q0 + w4 * QBLK) * PITCH + h * 128 + sub * 64;
;     const bf16_t* Kh = K + rowbase * PITCH + h * 128; const bf16_t* Vh = V + rowbase * PITCH + h * 128;
;     const unsigned lds0 = (unsigned)(uintptr_t)shm;
;     const bf16_t* ksrc = Kh + (long)lane * PITCH + wid * 8;
;     const bf16_t* vsrc = Vh + (long)(16 * (wid & 3) + (lane >> 2)) * PITCH + (wid >> 2) * 32 + (lane & 3) * 8;
;     const unsigned pdst = lds0 + wid * 1024;
;     ...
;     const lds_cptr kp0 = (lds_cptr)shm + sub * OFF_K1 + hi * 1024 + r32 * 16;
;     const lds_cptr vp0 = (lds_cptr)shm + OFF_V + ((lane >> 4) & 1) * 32 + (lane & 3) * 8 + (4 * hi + ((lane & 15) >> 2)) * 64;
;     const int NT = (q0 + QB2) / KVBLK;
;     const int mylast = q0 / KVBLK + (w4 >> 1);
;     DMA_T(0, 0); DMA_T(1, 1);
;     bf16x8 qr[4];
; #pragma unroll
;     for (int d0 = 0; d0 < 4; ++d0) qr[d0] = *reinterpret_cast<const bf16x8*>(&Qw[(long)r32 * PITCH + d0 * 16 + hi * 8]);
;     asm volatile("" : "+v"(qr[0]), "+v"(qr[1]), "+v"(qr[2]), "+v"(qr[3]));
;     f32x16 o[4]; o[0] = f32x16{}; o[1] = f32x16{}; o[2] = f32x16{}; o[3] = f32x16{};
;     float l_reg = 0.f;
;     int slot = 0, slot2 = 2;
;     for (int t = 0; t < NT; ++t) {
;         if (t + 1 < NT) { ATT_WAIT_BAR(4); } else { ATT_WAIT_BAR(0); }
;         if (t + 2 < NT) DMA_T(t + 2, slot2);
.LBB0_466:
	s_bitcmp0_b32 s34, 0
	v_readfirstlane_b32 s3, v164
	s_cselect_b32 s44, s6, s7
	s_bfe_u32 s31, s3, 0x20006
	s_lshl_b32 s30, s31, 14
	s_lshl_b32 s16, s44, 16
	s_or_b32 s16, s30, s16
	s_or_b32 s26, s0, s16
	s_mov_b32 s27, s1
	s_lshr_b32 s45, s3, 6
	s_lshr_b32 s39, s3, 8
	s_lshl_b32 s46, s44, 7
	s_lshl_b64 s[26:27], s[26:27], 1
	s_add_u32 s36, s85, s26
	s_addc_u32 s37, s86, s27
	s_lshl_b32 s35, s34, 7
	s_lshl_b32 s16, s34, 8
	s_add_u32 s38, s36, s16
	s_addc_u32 s41, s37, 0
	s_lshl_b32 s36, s39, 6
	s_lshl_b32 s40, s39, 7
	s_add_u32 s40, s38, s40
	s_addc_u32 s41, s41, 0
	s_add_u32 s42, s8, s16
	s_addc_u32 s43, s9, 0
	s_lshl_b32 s38, s31, 13
	v_or_b32_e32 v0, s38, v152
	v_lshl_add_u64 v[2:3], v[114:115], 0, s[16:17]
	s_lshl_b32 s16, s45, 13
	v_lshlrev_b32_e32 v0, 1, v0
	s_lshl_b32 s31, s45, 10
	s_mov_b32 s37, s17
	v_lshl_add_u64 v[2:3], v[2:3], 0, s[16:17]
	v_lshl_add_u64 v[4:5], s[42:43], 0, v[0:1]
	s_add_i32 s31, s31, 0
	s_mov_b32 s16, m0
	s_mov_b32 m0, s31
	s_nop 0
	global_load_lds_dwordx4 v[2:3], off
	s_mov_b32 m0, s16
	v_lshl_add_u64 v[4:5], v[4:5], 0, s[36:37]
	v_mov_b32_e32 v121, v1
	v_lshl_add_u64 v[6:7], v[2:3], 0, s[18:19]
	s_add_i32 s16, s31, 0x2000
	s_mov_b32 s42, m0
	s_mov_b32 m0, s16
	s_nop 0
	global_load_lds_dwordx4 v[6:7], off
	s_mov_b32 m0, s42
	v_lshl_add_u64 v[4:5], v[4:5], 0, v[120:121]
	s_add_i32 s16, s31, 0x4000
	s_mov_b32 s42, m0
	s_mov_b32 m0, s16
	s_nop 0
	global_load_lds_dwordx4 v[4:5], off
	s_mov_b32 m0, s42
	v_lshl_add_u64 v[6:7], v[4:5], 0, s[18:19]
	s_add_i32 s16, s31, 0x6000
	s_mov_b32 s42, m0
	s_mov_b32 m0, s16
	s_nop 0
	global_load_lds_dwordx4 v[6:7], off
	s_mov_b32 m0, s42
	s_add_i32 s16, s31, 0x8000
	v_lshl_add_u64 v[6:7], v[2:3], 0, s[20:21]
	s_mov_b32 s42, m0
	s_mov_b32 m0, s16
	s_nop 0
	global_load_lds_dwordx4 v[6:7], off
	s_mov_b32 m0, s42
	v_lshl_add_u64 v[2:3], v[2:3], 0, s[22:23]
	s_add_i32 s16, s31, 0xa000
	s_mov_b32 s42, m0
	s_mov_b32 m0, s16
	s_nop 0
	global_load_lds_dwordx4 v[2:3], off
	s_mov_b32 m0, s42
	v_lshl_add_u64 v[2:3], v[4:5], 0, s[20:21]
	s_add_i32 s16, s31, 0xc000
	s_mov_b32 s42, m0
	s_mov_b32 m0, s16
	s_nop 0
	global_load_lds_dwordx4 v[2:3], off
	s_mov_b32 m0, s42
	v_lshl_add_u64 v[2:3], v[4:5], 0, s[22:23]
	s_add_i32 s16, s31, 0xe000
	s_mov_b32 s42, m0
	s_mov_b32 m0, s16
	s_nop 0
	global_load_lds_dwordx4 v[2:3], off
	s_mov_b32 m0, s42
	global_load_dwordx4 v[98:101], v213, s[40:41] offset:96
	global_load_dwordx4 v[102:105], v213, s[40:41] offset:64
	global_load_dwordx4 v[106:109], v213, s[40:41] offset:32
	global_load_dwordx4 v[110:113], v213, s[40:41]
	v_mov_b32_e32 v14, v1
	v_mov_b32_e32 v15, v1
	v_mov_b32_e32 v2, v1
	v_mov_b32_e32 v3, v1
	v_mov_b32_e32 v4, v1
	v_mov_b32_e32 v5, v1
	v_mov_b32_e32 v6, v1
	v_mov_b32_e32 v7, v1
	v_mov_b32_e32 v8, v1
	v_mov_b32_e32 v9, v1
	v_mov_b32_e32 v10, v1
	v_mov_b32_e32 v11, v1
	v_mov_b32_e32 v12, v1
	v_mov_b32_e32 v13, v1
	s_addk_i32 s46, 0x80
	s_bfe_u32 s16, s45, 0x10001
	s_lshl_b32 s42, s44, 1
	s_lshr_b32 s44, s3, 2
	v_lshl_add_u64 v[16:17], s[36:37], 0, v[0:1]
	v_mov_b32_e32 v0, v1
	v_mov_b64_e32 v[64:65], v[14:15]
	v_mov_b64_e32 v[48:49], v[14:15]
	v_mov_b64_e32 v[32:33], v[14:15]
	s_lshr_b32 s43, s46, 6
	s_or_b32 s42, s16, s42
	s_lshr_b32 s16, s3, 6
	s_lshl_b32 s16, s16, 13
	v_lshl_add_u64 v[142:143], v[118:119], 0, v[16:17]
	v_mov_b64_e32 v[62:63], v[12:13]
	v_mov_b64_e32 v[60:61], v[10:11]
	v_mov_b64_e32 v[58:59], v[8:9]
	v_mov_b64_e32 v[56:57], v[6:7]
	v_mov_b64_e32 v[54:55], v[4:5]
	v_mov_b64_e32 v[52:53], v[2:3]
	v_mov_b64_e32 v[50:51], v[0:1]
	v_mov_b64_e32 v[46:47], v[12:13]
	v_mov_b64_e32 v[44:45], v[10:11]
	v_mov_b64_e32 v[42:43], v[8:9]
	v_mov_b64_e32 v[40:41], v[6:7]
	v_mov_b64_e32 v[38:39], v[4:5]
	v_mov_b64_e32 v[36:37], v[2:3]
	v_mov_b64_e32 v[34:35], v[0:1]
	v_mov_b64_e32 v[30:31], v[12:13]
	v_mov_b64_e32 v[28:29], v[10:11]
	v_mov_b64_e32 v[26:27], v[8:9]
	v_mov_b64_e32 v[24:25], v[6:7]
	v_mov_b64_e32 v[22:23], v[4:5]
	v_mov_b64_e32 v[20:21], v[2:3]
	v_mov_b64_e32 v[18:19], v[0:1]
	v_mov_b64_e32 v[16:17], v[14:15]
	v_mov_b32_e32 v121, 0
	s_mov_b32 s40, 0
	s_mov_b32 s41, 2
	v_lshl_add_u32 v123, s39, 13, v154
	s_add_i32 s44, s43, -2
	s_add_i32 s45, s43, -1
	v_lshl_add_u64 v[140:141], v[116:117], 0, s[16:17]
	v_mov_b64_e32 v[14:15], v[12:13]
	v_mov_b64_e32 v[12:13], v[10:11]
	v_mov_b64_e32 v[10:11], v[8:9]
	v_mov_b64_e32 v[8:9], v[6:7]
	v_mov_b64_e32 v[6:7], v[4:5]
	v_mov_b64_e32 v[4:5], v[2:3]
	v_mov_b64_e32 v[2:3], v[0:1]
	s_mov_b32 s16, 0
	s_waitcnt vmcnt(0)
	v_and_b32_e32 v0, 63, v164
	v_and_b32_e32 v125, 31, v0
	v_lshlrev_b32_e32 v123, 7, v125
	v_lshl_add_u32 v123, s39, 13, v123
	v_lshrrev_b32_e32 v125, 5, v0
	v_bfe_u32 v162, v0, 1, 1
	v_xor_b32_e32 v125, v125, v162
	v_lshl_add_u32 v123, v125, 4, v123
	v_bfe_u32 v125, v0, 2, 2
	v_lshl_add_u32 v123, v125, 5, v123
	v_mov_b32_e32 v253, 0
	s_cmp_lt_u32 s43, 3
	s_cbranch_scc1 .Latt_nok2
	s_add_i32 s46, s31, 0x10000
	s_mov_b32 m0, s46
	v_lshl_add_u64 v[162:163], v[140:141], 0, s[18:19]
	global_load_lds_dwordx4 v[140:141], off
	s_add_i32 m0, s46, 0x2000
	s_nop 0
	global_load_lds_dwordx4 v[162:163], off
	v_lshl_add_u64 v[140:141], v[140:141], 0, s[20:21]
; #define ATT_LAS __attribute__((address_space(3)))
; __device__ __forceinline__ unsigned cvtpk_s(float lo, float hi) { f32x2_t v = {lo, hi}; bf16x2_t b = __builtin_convertvector(v, bf16x2_t); return __builtin_bit_cast(unsigned, b); }
; #define ATT_WAIT_BAR(N) asm volatile("s_waitcnt vmcnt(" #N ") lgkmcnt(0)\n\ts_barrier" ::: "memory")
; __device__ __forceinline__ void attn_unit(const int b, const int h, const int qb, const bf16_t* Q, const bf16_t* K, const bf16_t* V, bf16_t* O, ATT_LAS char* shm, const float lam) {
;     ...
;     for (int t = 0; t < NT; ++t) {
;         if (t + 1 < NT) { ATT_WAIT_BAR(4); } else { ATT_WAIT_BAR(0); }
;         if (t + 2 < NT) DMA_T(t + 2, slot2);
;         if (t <= mylast) {
;             const lds_cptr kp = kp0 + slot * SLOTB; const lds_cptr vp = vp0 + slot * SLOTB;
;     ...
;             bf16x8 kf[8]; s16x4 va[8], vb[8];
; #pragma unroll
;             for (int d0 = 0; d0 < 4; ++d0) { kf[2 * d0] = *(const ATT_LAS bf16x8*)(kp + d0 * 2048); kf[2 * d0 + 1] = *(const ATT_LAS bf16x8*)(kp + d0 * 2048 + 512); }
;             ATT_VLOAD(va, 0);
;             ATT_SBAR();
;             f32x16 p0 = f32x16{}, p1 = f32x16{};
; #pragma unroll
;             for (int d0 = 0; d0 < 4; ++d0) { p0 = __builtin_amdgcn_mfma_f32_32x32x16_bf16(kf[2 * d0], qr[d0], p0, 0, 0, 0); p1 = __builtin_amdgcn_mfma_f32_32x32x16_bf16(kf[2 * d0 + 1], qr[d0], p1, 0, 0, 0); }
;             ATT_SBAR();
;             ATT_VLOAD(vb, 1);
;             ATT_SBAR();
; #pragma unroll
;             for (int r = 0; r < 16; ++r) { p0[r] = __builtin_amdgcn_exp2f(p0[r]); p1[r] = __builtin_amdgcn_exp2f(p1[r]); }
;             u32x4 pw[4];
; #pragma unroll
;             for (int j = 0; j < 4; ++j) { pw[0][j] = cvtpk_s(p0[2 * j], p0[2 * j + 1]); pw[1][j] = cvtpk_s(p0[8 + 2 * j], p0[9 + 2 * j]); pw[2][j] = cvtpk_s(p1[2 * j], p1[2 * j + 1]); pw[3][j] = cvtpk_s(p1[8 + 2 * j], p1[9 + 2 * j]); }
;             { float sa = 0.f, sb = 0.f;
; #pragma unroll
;               for (int r = 0; r < 16; ++r) { sa += p0[r]; sb += p1[r]; }
;               l_reg += sa + sb; }
;             ATT_PV(o[0], va);
;             ATT_SBAR();
;             ATT_VLOAD(va, 2);
;             ATT_SBAR();
;             ATT_PV(o[1], vb);
;             ATT_SBAR();
;             ATT_VLOAD(vb, 3);
;             ATT_SBAR();
;             ATT_PV(o[2], va);
;             ATT_SBAR();
;             ATT_PV(o[3], vb);
.Latt_nok2:
	s_nop 1
	v_readfirstlane_b32 s100, v140
	v_readfirstlane_b32 s101, v141
	s_nop 1
	s_bfe_u32 s36, s3, 0x10006
	s_lshl_b32 s36, s36, 6
	s_sub_u32 s100, s100, s36
	s_subb_u32 s101, s101, 0
	v_subrev_u32_e32 v140, s100, v140
	v_subrev_u32_e32 v142, s100, v142
	s_and_b32 s98, s42, 1
	s_barrier
	v_add_u32_e32 v0, 0, v123
	v_xor_b32_e32 v162, 32, v0
	v_xor_b32_e32 v163, 64, v0
	v_xor_b32_e32 v141, 0x60, v0
	ds_read_b128 v[232:235], v0
	ds_read_b128 v[236:239], v162
	s_waitcnt lgkmcnt(1)
	v_mfma_f32_32x32x16_bf16 v[66:81], v[232:235], v[110:113], 0
	ds_read_b128 v[232:235], v163
	s_waitcnt lgkmcnt(1)
	v_mfma_f32_32x32x16_bf16 v[66:81], v[236:239], v[106:109], v[66:81]
	ds_read_b128 v[236:239], v141
	s_waitcnt lgkmcnt(1)
	v_mfma_f32_32x32x16_bf16 v[66:81], v[232:235], v[102:105], v[66:81]
	ds_read_b128 v[232:235], v0 offset:4096
	s_waitcnt lgkmcnt(1)
	v_mfma_f32_32x32x16_bf16 v[66:81], v[236:239], v[98:101], v[66:81]
	ds_read_b128 v[236:239], v162 offset:4096
	s_waitcnt lgkmcnt(1)
	v_mfma_f32_32x32x16_bf16 v[82:97], v[232:235], v[110:113], 0
	ds_read_b128 v[232:235], v163 offset:4096
	s_waitcnt lgkmcnt(1)
	v_mfma_f32_32x32x16_bf16 v[82:97], v[236:239], v[106:109], v[82:97]
	ds_read_b128 v[236:239], v141 offset:4096
	s_waitcnt lgkmcnt(1)
	v_mfma_f32_32x32x16_bf16 v[82:97], v[232:235], v[102:105], v[82:97]
	s_waitcnt lgkmcnt(0)
	v_mfma_f32_32x32x16_bf16 v[82:97], v[236:239], v[98:101], v[82:97]
	s_nop 7
	v_exp_f32_e32 v66, v66
	v_exp_f32_e32 v67, v67
	v_exp_f32_e32 v68, v68
	v_exp_f32_e32 v69, v69
	v_add_f32_e32 v252, v66, v67
	v_exp_f32_e32 v70, v70
	v_exp_f32_e32 v71, v71
	v_add_f32_e32 v252, v252, v68
	v_add_f32_e32 v252, v252, v69
	v_exp_f32_e32 v72, v72
	v_exp_f32_e32 v73, v73
	v_add_f32_e32 v252, v252, v70
	v_add_f32_e32 v252, v252, v71
	v_exp_f32_e32 v74, v74
	v_exp_f32_e32 v75, v75
	v_add_f32_e32 v252, v252, v72
	v_add_f32_e32 v252, v252, v73
	v_cvt_pk_bf16_f32 v216, v66, v67
	v_cvt_pk_bf16_f32 v217, v68, v69
	v_cvt_pk_bf16_f32 v218, v70, v71
	v_cvt_pk_bf16_f32 v219, v72, v73
	v_exp_f32_e32 v76, v76
	v_exp_f32_e32 v77, v77
	v_add_f32_e32 v252, v252, v74
	v_add_f32_e32 v252, v252, v75
	v_exp_f32_e32 v78, v78
	v_exp_f32_e32 v79, v79
	v_add_f32_e32 v252, v252, v76
	v_add_f32_e32 v252, v252, v77
	v_exp_f32_e32 v80, v80
	v_exp_f32_e32 v81, v81
	v_add_f32_e32 v252, v252, v78
	v_add_f32_e32 v252, v252, v79
	v_add_f32_e32 v252, v252, v80
	v_add_f32_e32 v252, v252, v81
	v_cvt_pk_bf16_f32 v220, v74, v75
	v_cvt_pk_bf16_f32 v221, v76, v77
	v_cvt_pk_bf16_f32 v222, v78, v79
	v_cvt_pk_bf16_f32 v223, v80, v81
	v_add_f32_e32 v121, v121, v252
	s_nop 3
	s_cmp_lt_u32 s43, 3
	s_cbranch_scc1 .Latt_tail
.Latt_top:
	s_add_i32 s36, s16, 3
	s_cmp_lt_u32 s36, s43
	s_cselect_b32 s99, 1, 0
	s_waitcnt vmcnt(4)
	s_barrier
	s_add_i32 s36, s40, 1
	s_cmp_lg_u32 s40, 2
	s_cselect_b32 s36, s36, 0
	s_lshl_b32 s36, s36, 15
	v_add_u32_e32 v0, s36, v123
	v_xor_b32_e32 v162, 32, v0
	v_xor_b32_e32 v163, 64, v0
	v_xor_b32_e32 v141, 0x60, v0
	s_lshl_b32 s37, s40, 15
	v_add_u32_e32 v125, s37, v156
	s_add_i32 s46, s37, s31
	s_lshl_b32 s37, s41, 15
	s_add_i32 s37, s37, s31
	s_addk_i32 s37, 0x4000
	ds_read_b128 v[232:235], v0
	ds_read_b128 v[236:239], v162
	ds_read_b64_tr_b16 v[240:241], v125 offset:16384
	ds_read_b64_tr_b16 v[242:243], v125 offset:16896
	ds_read_b64_tr_b16 v[244:245], v125 offset:20480
	ds_read_b64_tr_b16 v[246:247], v125 offset:20992
	ds_read_b64_tr_b16 v[248:249], v125 offset:24576
	ds_read_b64_tr_b16 v[250:251], v125 offset:25088
	ds_read_b64_tr_b16 v[158:159], v125 offset:28672
	ds_read_b64_tr_b16 v[160:161], v125 offset:29184
	ds_read_b64_tr_b16 v[166:167], v125 offset:17408
	ds_read_b64_tr_b16 v[168:169], v125 offset:17920
	s_waitcnt lgkmcnt(11)
	v_mfma_f32_32x32x16_bf16 v[66:81], v[232:235], v[110:113], 0
	ds_read_b128 v[232:235], v163
	s_cmp_lg_u32 s99, 0
	s_cbranch_scc0 .Latt_m_nok
	s_mov_b32 m0, s46
	s_nop 0
	global_load_lds_dwordx4 v140, s[100:101]
	s_add_i32 m0, s46, 0x1f80
	s_nop 0
	global_load_lds_dwordx4 v140, s[100:101] offset:128
.Latt_m_nok:
	v_exp_f32_e32 v82, v82
	v_exp_f32_e32 v83, v83
	v_exp_f32_e32 v84, v84
	s_waitcnt lgkmcnt(9)
	v_mfma_f32_32x32x16_bf16 v[50:65], v[216:219], v[240:243], v[50:65]
	ds_read_b64_tr_b16 v[240:241], v125 offset:21504
	ds_read_b64_tr_b16 v[242:243], v125 offset:22016
	v_exp_f32_e32 v85, v85
	v_add_f32_e32 v253, v82, v83
	v_exp_f32_e32 v86, v86
	s_waitcnt lgkmcnt(9)
	v_mfma_f32_32x32x16_bf16 v[34:49], v[216:219], v[244:247], v[34:49]
	ds_read_b64_tr_b16 v[244:245], v125 offset:25600
	ds_read_b64_tr_b16 v[246:247], v125 offset:26112
	v_exp_f32_e32 v87, v87
	v_add_f32_e32 v253, v253, v84
	v_add_f32_e32 v253, v253, v85
	v_exp_f32_e32 v88, v88
	v_mfma_f32_32x32x16_bf16 v[66:81], v[236:239], v[106:109], v[66:81]
	ds_read_b128 v[236:239], v141
	s_mov_b32 m0, s37
	s_nop 0
	global_load_lds_dwordx4 v142, s[100:101]
	v_exp_f32_e32 v89, v89
	v_add_f32_e32 v253, v253, v86
	v_add_f32_e32 v253, v253, v87
	s_waitcnt lgkmcnt(10)
	v_mfma_f32_32x32x16_bf16 v[18:33], v[216:219], v[248:251], v[18:33]
	ds_read_b64_tr_b16 v[248:249], v125 offset:29696
	ds_read_b64_tr_b16 v[250:251], v125 offset:30208
	v_exp_f32_e32 v90, v90
	v_exp_f32_e32 v91, v91
	v_add_f32_e32 v253, v253, v88
	s_waitcnt lgkmcnt(10)
	v_mfma_f32_32x32x16_bf16 v[2:17], v[216:219], v[158:161], v[2:17]
	ds_read_b64_tr_b16 v[158:159], v125 offset:18432
	ds_read_b64_tr_b16 v[160:161], v125 offset:18944
	v_add_f32_e32 v253, v253, v89
	v_cvt_pk_bf16_f32 v224, v82, v83
	v_cvt_pk_bf16_f32 v225, v84, v85
	v_cvt_pk_bf16_f32 v226, v86, v87
	v_cvt_pk_bf16_f32 v227, v88, v89
	s_waitcnt lgkmcnt(9)
; __device__ __forceinline__ unsigned cvtpk_s(float lo, float hi) { f32x2_t v = {lo, hi}; bf16x2_t b = __builtin_convertvector(v, bf16x2_t); return __builtin_bit_cast(unsigned, b); }
; #define ATT_SBAR() __builtin_amdgcn_sched_barrier(0)
; #define ATT_VLOAD(dst, d0) do { _Pragma("unroll") for (int ks = 0; ks < 4; ++ks) { dst[2 * ks] = vtr(vp + (d0) * 4096 + ks * 1024); dst[2 * ks + 1] = vtr(vp + (d0) * 4096 + ks * 1024 + 512); } } while (0)
; #define ATT_PV(acc, src) do { _Pragma("unroll") for (int ks = 0; ks < 4; ++ks) { const bf16x8 vf_ = (bf16x8){src[2 * ks][0], src[2 * ks][1], src[2 * ks][2], src[2 * ks][3], src[2 * ks + 1][0], src[2 * ks + 1][1], src[2 * ks + 1][2], src[2 * ks + 1][3]}; \
;                 acc = __builtin_amdgcn_mfma_f32_32x32x16_bf16(__builtin_bit_cast(bf16x8, pw[ks]), vf_, acc, 0, 0, 0); } } while (0)
; __device__ __forceinline__ void attn_unit(const int b, const int h, const int qb, const bf16_t* Q, const bf16_t* K, const bf16_t* V, bf16_t* O, ATT_LAS char* shm, const float lam) {
;     ...
; #pragma unroll
;             for (int r = 0; r < 16; ++r) { p0[r] = __builtin_amdgcn_exp2f(p0[r]); p1[r] = __builtin_amdgcn_exp2f(p1[r]); }
;             u32x4 pw[4];
; #pragma unroll
;             for (int j = 0; j < 4; ++j) { pw[0][j] = cvtpk_s(p0[2 * j], p0[2 * j + 1]); pw[1][j] = cvtpk_s(p0[8 + 2 * j], p0[9 + 2 * j]); pw[2][j] = cvtpk_s(p1[2 * j], p1[2 * j + 1]); pw[3][j] = cvtpk_s(p1[8 + 2 * j], p1[9 + 2 * j]); }
;             { float sa = 0.f, sb = 0.f;
; #pragma unroll
;               for (int r = 0; r < 16; ++r) { sa += p0[r]; sb += p1[r]; }
;               l_reg += sa + sb; }
;             ATT_PV(o[0], va);
;             ATT_SBAR();
;             ATT_VLOAD(va, 2);
;             ATT_SBAR();
;             ATT_PV(o[1], vb);
;             ATT_SBAR();
;             ATT_VLOAD(vb, 3);
;             ATT_SBAR();
;             ATT_PV(o[2], va);
;             ATT_SBAR();
;             ATT_PV(o[3], vb);
;     ...
;         }
;         slot = (slot == NSLOT - 1) ? 0 : slot + 1; slot2 = (slot2 == NSLOT - 1) ? 0 : slot2 + 1;
	v_mfma_f32_32x32x16_bf16 v[66:81], v[232:235], v[102:105], v[66:81]
	ds_read_b128 v[232:235], v0 offset:4096
	s_add_i32 m0, s37, 0x1f80
	s_nop 0
	global_load_lds_dwordx4 v142, s[100:101] offset:128
	v_exp_f32_e32 v92, v92
	v_exp_f32_e32 v93, v93
	v_add_f32_e32 v253, v253, v90
	v_mfma_f32_32x32x16_bf16 v[50:65], v[220:223], v[166:169], v[50:65]
	ds_read_b64_tr_b16 v[166:167], v125 offset:22528
	ds_read_b64_tr_b16 v[168:169], v125 offset:23040
	v_add_f32_e32 v253, v253, v91
	v_exp_f32_e32 v94, v94
	v_exp_f32_e32 v95, v95
	s_waitcnt lgkmcnt(10)
	v_mfma_f32_32x32x16_bf16 v[34:49], v[220:223], v[240:243], v[34:49]
	ds_read_b64_tr_b16 v[240:241], v125 offset:26624
	ds_read_b64_tr_b16 v[242:243], v125 offset:27136
	v_add_f32_e32 v253, v253, v92
	v_add_f32_e32 v253, v253, v93
	v_exp_f32_e32 v96, v96
	v_exp_f32_e32 v97, v97
	s_waitcnt lgkmcnt(9)
	v_mfma_f32_32x32x16_bf16 v[66:81], v[236:239], v[98:101], v[66:81]
	ds_read_b128 v[236:239], v162 offset:4096
	v_add_f32_e32 v253, v253, v94
	v_add_f32_e32 v253, v253, v95
	v_add_f32_e32 v253, v253, v96
	v_add_f32_e32 v253, v253, v97
	v_mfma_f32_32x32x16_bf16 v[18:33], v[220:223], v[244:247], v[18:33]
	ds_read_b64_tr_b16 v[244:245], v125 offset:30720
	ds_read_b64_tr_b16 v[246:247], v125 offset:31232
	v_cvt_pk_bf16_f32 v228, v90, v91
	v_cvt_pk_bf16_f32 v229, v92, v93
	v_cvt_pk_bf16_f32 v230, v94, v95
	v_cvt_pk_bf16_f32 v231, v96, v97
	v_add_f32_e32 v121, v121, v253
	s_waitcnt lgkmcnt(10)
	v_mfma_f32_32x32x16_bf16 v[2:17], v[220:223], v[248:251], v[2:17]
	ds_read_b64_tr_b16 v[248:249], v125 offset:19456
	ds_read_b64_tr_b16 v[250:251], v125 offset:19968
	v_exp_f32_e32 v66, v66
	v_exp_f32_e32 v67, v67
	v_exp_f32_e32 v68, v68
	s_waitcnt lgkmcnt(9)
	v_mfma_f32_32x32x16_bf16 v[82:97], v[232:235], v[110:113], 0
	ds_read_b128 v[232:235], v163 offset:4096
	v_exp_f32_e32 v69, v69
	v_add_f32_e32 v252, v66, v67
	v_mfma_f32_32x32x16_bf16 v[50:65], v[224:227], v[158:161], v[50:65]
	ds_read_b64_tr_b16 v[158:159], v125 offset:23552
	ds_read_b64_tr_b16 v[160:161], v125 offset:24064
	v_exp_f32_e32 v70, v70
	v_exp_f32_e32 v71, v71
	s_waitcnt lgkmcnt(10)
	v_mfma_f32_32x32x16_bf16 v[34:49], v[224:227], v[166:169], v[34:49]
	ds_read_b64_tr_b16 v[166:167], v125 offset:27648
	ds_read_b64_tr_b16 v[168:169], v125 offset:28160
	v_add_f32_e32 v252, v252, v68
	v_add_f32_e32 v252, v252, v69
	v_exp_f32_e32 v72, v72
	v_exp_f32_e32 v73, v73
	s_waitcnt lgkmcnt(9)
	v_mfma_f32_32x32x16_bf16 v[82:97], v[236:239], v[106:109], v[82:97]
	ds_read_b128 v[236:239], v141 offset:4096
	v_add_f32_e32 v252, v252, v70
	v_add_f32_e32 v252, v252, v71
	v_exp_f32_e32 v74, v74
	v_mfma_f32_32x32x16_bf16 v[18:33], v[224:227], v[240:243], v[18:33]
	ds_read_b64_tr_b16 v[240:241], v125 offset:31744
	ds_read_b64_tr_b16 v[242:243], v125 offset:32256
	v_exp_f32_e32 v75, v75
	v_add_f32_e32 v252, v252, v72
	s_waitcnt lgkmcnt(10)
	v_mfma_f32_32x32x16_bf16 v[2:17], v[224:227], v[244:247], v[2:17]
	v_add_f32_e32 v252, v252, v73
	v_cvt_pk_bf16_f32 v216, v66, v67
	v_cvt_pk_bf16_f32 v217, v68, v69
	v_cvt_pk_bf16_f32 v218, v70, v71
	v_cvt_pk_bf16_f32 v219, v72, v73
	s_waitcnt lgkmcnt(7)
	v_mfma_f32_32x32x16_bf16 v[82:97], v[232:235], v[102:105], v[82:97]
	v_exp_f32_e32 v76, v76
	v_exp_f32_e32 v77, v77
	v_mfma_f32_32x32x16_bf16 v[50:65], v[228:231], v[248:251], v[50:65]
	v_add_f32_e32 v252, v252, v74
	v_add_f32_e32 v252, v252, v75
	v_exp_f32_e32 v78, v78
	s_waitcnt lgkmcnt(5)
	v_mfma_f32_32x32x16_bf16 v[34:49], v[228:231], v[158:161], v[34:49]
	v_exp_f32_e32 v79, v79
	v_add_f32_e32 v252, v252, v76
	v_add_f32_e32 v252, v252, v77
	v_exp_f32_e32 v80, v80
	s_waitcnt lgkmcnt(2)
	v_mfma_f32_32x32x16_bf16 v[82:97], v[236:239], v[98:101], v[82:97]
	v_exp_f32_e32 v81, v81
	v_add_f32_e32 v252, v252, v78
	v_mfma_f32_32x32x16_bf16 v[18:33], v[228:231], v[166:169], v[18:33]
	v_add_f32_e32 v252, v252, v79
	v_add_f32_e32 v252, v252, v80
	v_add_f32_e32 v252, v252, v81
	v_cvt_pk_bf16_f32 v220, v74, v75
	s_waitcnt lgkmcnt(0)
	v_mfma_f32_32x32x16_bf16 v[2:17], v[228:231], v[240:243], v[2:17]
	v_cvt_pk_bf16_f32 v221, v76, v77
	v_cvt_pk_bf16_f32 v222, v78, v79
	v_cvt_pk_bf16_f32 v223, v80, v81
	v_add_f32_e32 v121, v121, v252
	s_add_i32 s16, s16, 1
	s_add_i32 s36, s40, 1
	s_cmp_lg_u32 s40, 2
	s_cselect_b32 s40, s36, 0
	s_add_i32 s36, s41, 1
	s_cmp_lg_u32 s41, 2
	s_cselect_b32 s41, s36, 0
	s_add_u32 s100, s100, 0x10000
	s_addc_u32 s101, s101, 0
	s_cmp_lt_u32 s16, s44
	s_cbranch_scc1 .Latt_top
; #define ATT_LAS __attribute__((address_space(3)))
; __device__ __forceinline__ unsigned cvtpk_s(float lo, float hi) { f32x2_t v = {lo, hi}; bf16x2_t b = __builtin_convertvector(v, bf16x2_t); return __builtin_bit_cast(unsigned, b); }
; #define ATT_WAIT_BAR(N) asm volatile("s_waitcnt vmcnt(" #N ") lgkmcnt(0)\n\ts_barrier" ::: "memory")
; #define ATT_SBAR() __builtin_amdgcn_sched_barrier(0)
; __device__ __forceinline__ void attn_unit(const int b, const int h, const int qb, const bf16_t* Q, const bf16_t* K, const bf16_t* V, bf16_t* O, ATT_LAS char* shm, const float lam) {
;     ...
;         if (t + 1 < NT) { ATT_WAIT_BAR(4); } else { ATT_WAIT_BAR(0); }
;         if (t + 2 < NT) DMA_T(t + 2, slot2);
;         if (t <= mylast) {
;             const lds_cptr kp = kp0 + slot * SLOTB; const lds_cptr vp = vp0 + slot * SLOTB;
;     ...
;             bf16x8 kf[8]; s16x4 va[8], vb[8];
; #pragma unroll
;             for (int d0 = 0; d0 < 4; ++d0) { kf[2 * d0] = *(const ATT_LAS bf16x8*)(kp + d0 * 2048); kf[2 * d0 + 1] = *(const ATT_LAS bf16x8*)(kp + d0 * 2048 + 512); }
;             ATT_VLOAD(va, 0);
;             ATT_SBAR();
;             f32x16 p0 = f32x16{}, p1 = f32x16{};
; #pragma unroll
;             for (int d0 = 0; d0 < 4; ++d0) { p0 = __builtin_amdgcn_mfma_f32_32x32x16_bf16(kf[2 * d0], qr[d0], p0, 0, 0, 0); p1 = __builtin_amdgcn_mfma_f32_32x32x16_bf16(kf[2 * d0 + 1], qr[d0], p1, 0, 0, 0); }
;             ATT_SBAR();
;             ATT_VLOAD(vb, 1);
;             ATT_SBAR();
; #pragma unroll
;             for (int r = 0; r < 16; ++r) { p0[r] = __builtin_amdgcn_exp2f(p0[r]); p1[r] = __builtin_amdgcn_exp2f(p1[r]); }
;             u32x4 pw[4];
; #pragma unroll
;             for (int j = 0; j < 4; ++j) { pw[0][j] = cvtpk_s(p0[2 * j], p0[2 * j + 1]); pw[1][j] = cvtpk_s(p0[8 + 2 * j], p0[9 + 2 * j]); pw[2][j] = cvtpk_s(p1[2 * j], p1[2 * j + 1]); pw[3][j] = cvtpk_s(p1[8 + 2 * j], p1[9 + 2 * j]); }
;             { float sa = 0.f, sb = 0.f;
; #pragma unroll
;               for (int r = 0; r < 16; ++r) { sa += p0[r]; sb += p1[r]; }
;               l_reg += sa + sb; }
;             ATT_PV(o[0], va);
;             ATT_SBAR();
;             ATT_VLOAD(va, 2);
;             ATT_SBAR();
;             ATT_PV(o[1], vb);
;             ATT_SBAR();
;             ATT_VLOAD(vb, 3);
;             ATT_SBAR();
;             ATT_PV(o[2], va);
;             ATT_SBAR();
;             ATT_PV(o[3], vb);
.Latt_tail:
	s_waitcnt vmcnt(2)
	s_barrier
	s_cmp_lg_u32 s98, 0
	s_cbranch_scc0 .Latt_low
	s_add_i32 s36, s40, 1
	s_cmp_lg_u32 s40, 2
	s_cselect_b32 s36, s36, 0
	s_lshl_b32 s36, s36, 15
	v_add_u32_e32 v0, s36, v123
	v_xor_b32_e32 v162, 32, v0
	v_xor_b32_e32 v163, 64, v0
	v_xor_b32_e32 v141, 0x60, v0
	s_lshl_b32 s37, s40, 15
	v_add_u32_e32 v125, s37, v156
	ds_read_b128 v[232:235], v0
	ds_read_b128 v[236:239], v162
	ds_read_b64_tr_b16 v[240:241], v125 offset:16384
	ds_read_b64_tr_b16 v[242:243], v125 offset:16896
	ds_read_b64_tr_b16 v[244:245], v125 offset:20480
	ds_read_b64_tr_b16 v[246:247], v125 offset:20992
	ds_read_b64_tr_b16 v[248:249], v125 offset:24576
	ds_read_b64_tr_b16 v[250:251], v125 offset:25088
	ds_read_b64_tr_b16 v[158:159], v125 offset:28672
	ds_read_b64_tr_b16 v[160:161], v125 offset:29184
	ds_read_b64_tr_b16 v[166:167], v125 offset:17408
	ds_read_b64_tr_b16 v[168:169], v125 offset:17920
	s_waitcnt lgkmcnt(11)
	v_mfma_f32_32x32x16_bf16 v[66:81], v[232:235], v[110:113], 0
	ds_read_b128 v[232:235], v163
	v_exp_f32_e32 v82, v82
	v_exp_f32_e32 v83, v83
	v_exp_f32_e32 v84, v84
	s_waitcnt lgkmcnt(9)
	v_mfma_f32_32x32x16_bf16 v[50:65], v[216:219], v[240:243], v[50:65]
	ds_read_b64_tr_b16 v[240:241], v125 offset:21504
	ds_read_b64_tr_b16 v[242:243], v125 offset:22016
	v_exp_f32_e32 v85, v85
	v_add_f32_e32 v253, v82, v83
	v_exp_f32_e32 v86, v86
	s_waitcnt lgkmcnt(9)
	v_mfma_f32_32x32x16_bf16 v[34:49], v[216:219], v[244:247], v[34:49]
	ds_read_b64_tr_b16 v[244:245], v125 offset:25600
	ds_read_b64_tr_b16 v[246:247], v125 offset:26112
	v_exp_f32_e32 v87, v87
	v_add_f32_e32 v253, v253, v84
	v_add_f32_e32 v253, v253, v85
	v_exp_f32_e32 v88, v88
	v_mfma_f32_32x32x16_bf16 v[66:81], v[236:239], v[106:109], v[66:81]
	ds_read_b128 v[236:239], v141
	v_exp_f32_e32 v89, v89
	v_add_f32_e32 v253, v253, v86
	v_add_f32_e32 v253, v253, v87
	s_waitcnt lgkmcnt(10)
	v_mfma_f32_32x32x16_bf16 v[18:33], v[216:219], v[248:251], v[18:33]
	ds_read_b64_tr_b16 v[248:249], v125 offset:29696
	ds_read_b64_tr_b16 v[250:251], v125 offset:30208
	v_exp_f32_e32 v90, v90
	v_exp_f32_e32 v91, v91
	v_add_f32_e32 v253, v253, v88
	s_waitcnt lgkmcnt(10)
	v_mfma_f32_32x32x16_bf16 v[2:17], v[216:219], v[158:161], v[2:17]
	ds_read_b64_tr_b16 v[158:159], v125 offset:18432
	ds_read_b64_tr_b16 v[160:161], v125 offset:18944
	v_add_f32_e32 v253, v253, v89
	v_cvt_pk_bf16_f32 v224, v82, v83
	v_cvt_pk_bf16_f32 v225, v84, v85
	v_cvt_pk_bf16_f32 v226, v86, v87
	v_cvt_pk_bf16_f32 v227, v88, v89
	s_waitcnt lgkmcnt(9)
	v_mfma_f32_32x32x16_bf16 v[66:81], v[232:235], v[102:105], v[66:81]
	ds_read_b128 v[232:235], v0 offset:4096
	v_exp_f32_e32 v92, v92
	v_exp_f32_e32 v93, v93
	v_add_f32_e32 v253, v253, v90
	v_mfma_f32_32x32x16_bf16 v[50:65], v[220:223], v[166:169], v[50:65]
	ds_read_b64_tr_b16 v[166:167], v125 offset:22528
	ds_read_b64_tr_b16 v[168:169], v125 offset:23040
	v_add_f32_e32 v253, v253, v91
	v_exp_f32_e32 v94, v94
	v_exp_f32_e32 v95, v95
	s_waitcnt lgkmcnt(10)
	v_mfma_f32_32x32x16_bf16 v[34:49], v[220:223], v[240:243], v[34:49]
	ds_read_b64_tr_b16 v[240:241], v125 offset:26624
	ds_read_b64_tr_b16 v[242:243], v125 offset:27136
	v_add_f32_e32 v253, v253, v92
	v_add_f32_e32 v253, v253, v93
	v_exp_f32_e32 v96, v96
	v_exp_f32_e32 v97, v97
	s_waitcnt lgkmcnt(9)
	v_mfma_f32_32x32x16_bf16 v[66:81], v[236:239], v[98:101], v[66:81]
	ds_read_b128 v[236:239], v162 offset:4096
	v_add_f32_e32 v253, v253, v94
	v_add_f32_e32 v253, v253, v95
	v_add_f32_e32 v253, v253, v96
	v_add_f32_e32 v253, v253, v97
	v_mfma_f32_32x32x16_bf16 v[18:33], v[220:223], v[244:247], v[18:33]
	ds_read_b64_tr_b16 v[244:245], v125 offset:30720
	ds_read_b64_tr_b16 v[246:247], v125 offset:31232
	v_cvt_pk_bf16_f32 v228, v90, v91
	v_cvt_pk_bf16_f32 v229, v92, v93
	v_cvt_pk_bf16_f32 v230, v94, v95
	v_cvt_pk_bf16_f32 v231, v96, v97
	v_add_f32_e32 v121, v121, v253
	s_waitcnt lgkmcnt(10)
	v_mfma_f32_32x32x16_bf16 v[2:17], v[220:223], v[248:251], v[2:17]
	ds_read_b64_tr_b16 v[248:249], v125 offset:19456
	ds_read_b64_tr_b16 v[250:251], v125 offset:19968
	v_exp_f32_e32 v66, v66
	v_exp_f32_e32 v67, v67
	v_exp_f32_e32 v68, v68
	s_waitcnt lgkmcnt(9)
	v_mfma_f32_32x32x16_bf16 v[82:97], v[232:235], v[110:113], 0
	ds_read_b128 v[232:235], v163 offset:4096
	v_exp_f32_e32 v69, v69
	v_add_f32_e32 v252, v66, v67
	v_mfma_f32_32x32x16_bf16 v[50:65], v[224:227], v[158:161], v[50:65]
	ds_read_b64_tr_b16 v[158:159], v125 offset:23552
	ds_read_b64_tr_b16 v[160:161], v125 offset:24064
	v_exp_f32_e32 v70, v70
	v_exp_f32_e32 v71, v71
	s_waitcnt lgkmcnt(10)
	v_mfma_f32_32x32x16_bf16 v[34:49], v[224:227], v[166:169], v[34:49]
	ds_read_b64_tr_b16 v[166:167], v125 offset:27648
	ds_read_b64_tr_b16 v[168:169], v125 offset:28160
	v_add_f32_e32 v252, v252, v68
	v_add_f32_e32 v252, v252, v69
	v_exp_f32_e32 v72, v72
	v_exp_f32_e32 v73, v73
	s_waitcnt lgkmcnt(9)
	v_mfma_f32_32x32x16_bf16 v[82:97], v[236:239], v[106:109], v[82:97]
	ds_read_b128 v[236:239], v141 offset:4096
	v_add_f32_e32 v252, v252, v70
	v_add_f32_e32 v252, v252, v71
	v_exp_f32_e32 v74, v74
	v_mfma_f32_32x32x16_bf16 v[18:33], v[224:227], v[240:243], v[18:33]
	ds_read_b64_tr_b16 v[240:241], v125 offset:31744
	ds_read_b64_tr_b16 v[242:243], v125 offset:32256
	v_exp_f32_e32 v75, v75
	v_add_f32_e32 v252, v252, v72
	s_waitcnt lgkmcnt(10)
	v_mfma_f32_32x32x16_bf16 v[2:17], v[224:227], v[244:247], v[2:17]
	v_add_f32_e32 v252, v252, v73
	v_cvt_pk_bf16_f32 v216, v66, v67
	v_cvt_pk_bf16_f32 v217, v68, v69
	v_cvt_pk_bf16_f32 v218, v70, v71
	v_cvt_pk_bf16_f32 v219, v72, v73
	s_waitcnt lgkmcnt(7)
	v_mfma_f32_32x32x16_bf16 v[82:97], v[232:235], v[102:105], v[82:97]
	v_exp_f32_e32 v76, v76
	v_exp_f32_e32 v77, v77
	v_mfma_f32_32x32x16_bf16 v[50:65], v[228:231], v[248:251], v[50:65]
	v_add_f32_e32 v252, v252, v74
	v_add_f32_e32 v252, v252, v75
	v_exp_f32_e32 v78, v78
	s_waitcnt lgkmcnt(5)
	v_mfma_f32_32x32x16_bf16 v[34:49], v[228:231], v[158:161], v[34:49]
	v_exp_f32_e32 v79, v79
	v_add_f32_e32 v252, v252, v76
	v_add_f32_e32 v252, v252, v77
	v_exp_f32_e32 v80, v80
	s_waitcnt lgkmcnt(2)
	v_mfma_f32_32x32x16_bf16 v[82:97], v[236:239], v[98:101], v[82:97]
	v_exp_f32_e32 v81, v81
	v_add_f32_e32 v252, v252, v78
	v_mfma_f32_32x32x16_bf16 v[18:33], v[228:231], v[166:169], v[18:33]
	v_add_f32_e32 v252, v252, v79
	v_add_f32_e32 v252, v252, v80
	v_add_f32_e32 v252, v252, v81
	v_cvt_pk_bf16_f32 v220, v74, v75
	s_waitcnt lgkmcnt(0)
	v_mfma_f32_32x32x16_bf16 v[2:17], v[228:231], v[240:243], v[2:17]
	v_cvt_pk_bf16_f32 v221, v76, v77
	v_cvt_pk_bf16_f32 v222, v78, v79
	v_cvt_pk_bf16_f32 v223, v80, v81
	v_add_f32_e32 v121, v121, v252
	s_add_i32 s16, s16, 1
	s_add_i32 s36, s40, 1
	s_cmp_lg_u32 s40, 2
	s_cselect_b32 s40, s36, 0
	s_waitcnt vmcnt(0)
	s_barrier
; __device__ __forceinline__ unsigned cvtpk_s(float lo, float hi) { f32x2_t v = {lo, hi}; bf16x2_t b = __builtin_convertvector(v, bf16x2_t); return __builtin_bit_cast(unsigned, b); }
; #define ATT_SBAR() __builtin_amdgcn_sched_barrier(0)
; #define ATT_VLOAD(dst, d0) do { _Pragma("unroll") for (int ks = 0; ks < 4; ++ks) { dst[2 * ks] = vtr(vp + (d0) * 4096 + ks * 1024); dst[2 * ks + 1] = vtr(vp + (d0) * 4096 + ks * 1024 + 512); } } while (0)
; #define ATT_PV(acc, src) do { _Pragma("unroll") for (int ks = 0; ks < 4; ++ks) { const bf16x8 vf_ = (bf16x8){src[2 * ks][0], src[2 * ks][1], src[2 * ks][2], src[2 * ks][3], src[2 * ks + 1][0], src[2 * ks + 1][1], src[2 * ks + 1][2], src[2 * ks + 1][3]}; \
;                 acc = __builtin_amdgcn_mfma_f32_32x32x16_bf16(__builtin_bit_cast(bf16x8, pw[ks]), vf_, acc, 0, 0, 0); } } while (0)
; __device__ __forceinline__ void attn_unit(const int b, const int h, const int qb, const bf16_t* Q, const bf16_t* K, const bf16_t* V, bf16_t* O, ATT_LAS char* shm, const float lam) {
;     ...
;             for (int r = 0; r < 16; ++r) { p0[r] = __builtin_amdgcn_exp2f(p0[r]); p1[r] = __builtin_amdgcn_exp2f(p1[r]); }
;             u32x4 pw[4];
; #pragma unroll
;             for (int j = 0; j < 4; ++j) { pw[0][j] = cvtpk_s(p0[2 * j], p0[2 * j + 1]); pw[1][j] = cvtpk_s(p0[8 + 2 * j], p0[9 + 2 * j]); pw[2][j] = cvtpk_s(p1[2 * j], p1[2 * j + 1]); pw[3][j] = cvtpk_s(p1[8 + 2 * j], p1[9 + 2 * j]); }
;             { float sa = 0.f, sb = 0.f;
; #pragma unroll
;               for (int r = 0; r < 16; ++r) { sa += p0[r]; sb += p1[r]; }
;               l_reg += sa + sb; }
;             ATT_PV(o[0], va);
;             ATT_SBAR();
;             ATT_VLOAD(va, 2);
;             ATT_SBAR();
;             ATT_PV(o[1], vb);
;             ATT_SBAR();
;             ATT_VLOAD(vb, 3);
;             ATT_SBAR();
;             ATT_PV(o[2], va);
;             ATT_SBAR();
;             ATT_PV(o[3], vb);
	s_lshl_b32 s37, s40, 15
	v_add_u32_e32 v125, s37, v156
	ds_read_b64_tr_b16 v[240:241], v125 offset:16384
	ds_read_b64_tr_b16 v[242:243], v125 offset:16896
	ds_read_b64_tr_b16 v[244:245], v125 offset:20480
	ds_read_b64_tr_b16 v[246:247], v125 offset:20992
	ds_read_b64_tr_b16 v[248:249], v125 offset:24576
	ds_read_b64_tr_b16 v[250:251], v125 offset:25088
	ds_read_b64_tr_b16 v[158:159], v125 offset:28672
	ds_read_b64_tr_b16 v[160:161], v125 offset:29184
	ds_read_b64_tr_b16 v[166:167], v125 offset:17408
	ds_read_b64_tr_b16 v[168:169], v125 offset:17920
	s_waitcnt lgkmcnt(8)
	v_mfma_f32_32x32x16_bf16 v[50:65], v[216:219], v[240:243], v[50:65]
	ds_read_b64_tr_b16 v[240:241], v125 offset:21504
	ds_read_b64_tr_b16 v[242:243], v125 offset:22016
	v_exp_f32_e32 v82, v82
	v_exp_f32_e32 v83, v83
	v_exp_f32_e32 v84, v84
	v_exp_f32_e32 v85, v85
	s_waitcnt lgkmcnt(8)
	v_mfma_f32_32x32x16_bf16 v[34:49], v[216:219], v[244:247], v[34:49]
	ds_read_b64_tr_b16 v[244:245], v125 offset:25600
	ds_read_b64_tr_b16 v[246:247], v125 offset:26112
	v_add_f32_e32 v253, v82, v83
	v_exp_f32_e32 v86, v86
	v_exp_f32_e32 v87, v87
	v_add_f32_e32 v253, v253, v84
	s_waitcnt lgkmcnt(8)
	v_mfma_f32_32x32x16_bf16 v[18:33], v[216:219], v[248:251], v[18:33]
	ds_read_b64_tr_b16 v[248:249], v125 offset:29696
	ds_read_b64_tr_b16 v[250:251], v125 offset:30208
	v_add_f32_e32 v253, v253, v85
	v_exp_f32_e32 v88, v88
	v_exp_f32_e32 v89, v89
	v_add_f32_e32 v253, v253, v86
	v_add_f32_e32 v253, v253, v87
	s_waitcnt lgkmcnt(8)
	v_mfma_f32_32x32x16_bf16 v[2:17], v[216:219], v[158:161], v[2:17]
	ds_read_b64_tr_b16 v[158:159], v125 offset:18432
	ds_read_b64_tr_b16 v[160:161], v125 offset:18944
	v_exp_f32_e32 v90, v90
	v_exp_f32_e32 v91, v91
	v_add_f32_e32 v253, v253, v88
	v_add_f32_e32 v253, v253, v89
	v_cvt_pk_bf16_f32 v224, v82, v83
	s_waitcnt lgkmcnt(8)
	v_mfma_f32_32x32x16_bf16 v[50:65], v[220:223], v[166:169], v[50:65]
	ds_read_b64_tr_b16 v[166:167], v125 offset:22528
	ds_read_b64_tr_b16 v[168:169], v125 offset:23040
	v_cvt_pk_bf16_f32 v225, v84, v85
	v_cvt_pk_bf16_f32 v226, v86, v87
	v_cvt_pk_bf16_f32 v227, v88, v89
	v_exp_f32_e32 v92, v92
	v_exp_f32_e32 v93, v93
	s_waitcnt lgkmcnt(8)
	v_mfma_f32_32x32x16_bf16 v[34:49], v[220:223], v[240:243], v[34:49]
	ds_read_b64_tr_b16 v[240:241], v125 offset:26624
	ds_read_b64_tr_b16 v[242:243], v125 offset:27136
	v_add_f32_e32 v253, v253, v90
	v_add_f32_e32 v253, v253, v91
	v_exp_f32_e32 v94, v94
	v_exp_f32_e32 v95, v95
	v_add_f32_e32 v253, v253, v92
	s_waitcnt lgkmcnt(8)
	v_mfma_f32_32x32x16_bf16 v[18:33], v[220:223], v[244:247], v[18:33]
	ds_read_b64_tr_b16 v[244:245], v125 offset:30720
	ds_read_b64_tr_b16 v[246:247], v125 offset:31232
	v_add_f32_e32 v253, v253, v93
	v_exp_f32_e32 v96, v96
	v_exp_f32_e32 v97, v97
	v_add_f32_e32 v253, v253, v94
	v_add_f32_e32 v253, v253, v95
	s_waitcnt lgkmcnt(8)
	v_mfma_f32_32x32x16_bf16 v[2:17], v[220:223], v[248:251], v[2:17]
	ds_read_b64_tr_b16 v[248:249], v125 offset:19456
	ds_read_b64_tr_b16 v[250:251], v125 offset:19968
	v_add_f32_e32 v253, v253, v96
	v_add_f32_e32 v253, v253, v97
	v_cvt_pk_bf16_f32 v228, v90, v91
	v_cvt_pk_bf16_f32 v229, v92, v93
	v_cvt_pk_bf16_f32 v230, v94, v95
	v_cvt_pk_bf16_f32 v231, v96, v97
	v_add_f32_e32 v121, v121, v253
	s_waitcnt lgkmcnt(8)
	v_mfma_f32_32x32x16_bf16 v[50:65], v[224:227], v[158:161], v[50:65]
	ds_read_b64_tr_b16 v[158:159], v125 offset:23552
	ds_read_b64_tr_b16 v[160:161], v125 offset:24064
	s_waitcnt lgkmcnt(8)
	v_mfma_f32_32x32x16_bf16 v[34:49], v[224:227], v[166:169], v[34:49]
	ds_read_b64_tr_b16 v[166:167], v125 offset:27648
	ds_read_b64_tr_b16 v[168:169], v125 offset:28160
	s_waitcnt lgkmcnt(8)
	v_mfma_f32_32x32x16_bf16 v[18:33], v[224:227], v[240:243], v[18:33]
	ds_read_b64_tr_b16 v[240:241], v125 offset:31744
	ds_read_b64_tr_b16 v[242:243], v125 offset:32256
	s_waitcnt lgkmcnt(8)
	v_mfma_f32_32x32x16_bf16 v[2:17], v[224:227], v[244:247], v[2:17]
	s_waitcnt lgkmcnt(6)
	v_mfma_f32_32x32x16_bf16 v[50:65], v[228:231], v[248:251], v[50:65]
	s_waitcnt lgkmcnt(4)
	v_mfma_f32_32x32x16_bf16 v[34:49], v[228:231], v[158:161], v[34:49]
	s_waitcnt lgkmcnt(2)
	v_mfma_f32_32x32x16_bf16 v[18:33], v[228:231], v[166:169], v[18:33]
	s_waitcnt lgkmcnt(0)
	v_mfma_f32_32x32x16_bf16 v[2:17], v[228:231], v[240:243], v[2:17]
	s_branch .LBB0_474
; __device__ __forceinline__ unsigned cvtpk_s(float lo, float hi) { f32x2_t v = {lo, hi}; bf16x2_t b = __builtin_convertvector(v, bf16x2_t); return __builtin_bit_cast(unsigned, b); }
; #define ATT_SBAR() __builtin_amdgcn_sched_barrier(0)
; #define ATT_VLOAD(dst, d0) do { _Pragma("unroll") for (int ks = 0; ks < 4; ++ks) { dst[2 * ks] = vtr(vp + (d0) * 4096 + ks * 1024); dst[2 * ks + 1] = vtr(vp + (d0) * 4096 + ks * 1024 + 512); } } while (0)
; #define ATT_PV(acc, src) do { _Pragma("unroll") for (int ks = 0; ks < 4; ++ks) { const bf16x8 vf_ = (bf16x8){src[2 * ks][0], src[2 * ks][1], src[2 * ks][2], src[2 * ks][3], src[2 * ks + 1][0], src[2 * ks + 1][1], src[2 * ks + 1][2], src[2 * ks + 1][3]}; \
;                 acc = __builtin_amdgcn_mfma_f32_32x32x16_bf16(__builtin_bit_cast(bf16x8, pw[ks]), vf_, acc, 0, 0, 0); } } while (0)
; __device__ __forceinline__ void attn_unit(const int b, const int h, const int qb, const bf16_t* Q, const bf16_t* K, const bf16_t* V, bf16_t* O, ATT_LAS char* shm, const float lam) {
;     ...
;             for (int r = 0; r < 16; ++r) { p0[r] = __builtin_amdgcn_exp2f(p0[r]); p1[r] = __builtin_amdgcn_exp2f(p1[r]); }
;             u32x4 pw[4];
; #pragma unroll
;             for (int j = 0; j < 4; ++j) { pw[0][j] = cvtpk_s(p0[2 * j], p0[2 * j + 1]); pw[1][j] = cvtpk_s(p0[8 + 2 * j], p0[9 + 2 * j]); pw[2][j] = cvtpk_s(p1[2 * j], p1[2 * j + 1]); pw[3][j] = cvtpk_s(p1[8 + 2 * j], p1[9 + 2 * j]); }
;             { float sa = 0.f, sb = 0.f;
; #pragma unroll
;               for (int r = 0; r < 16; ++r) { sa += p0[r]; sb += p1[r]; }
;               l_reg += sa + sb; }
;             ATT_PV(o[0], va);
;             ATT_SBAR();
;             ATT_VLOAD(va, 2);
;             ATT_SBAR();
;             ATT_PV(o[1], vb);
;             ATT_SBAR();
;             ATT_VLOAD(vb, 3);
;             ATT_SBAR();
;             ATT_PV(o[2], va);
;             ATT_SBAR();
;             ATT_PV(o[3], vb);
.Latt_low:
	s_lshl_b32 s37, s40, 15
	v_add_u32_e32 v125, s37, v156
	ds_read_b64_tr_b16 v[240:241], v125 offset:16384
	ds_read_b64_tr_b16 v[242:243], v125 offset:16896
	ds_read_b64_tr_b16 v[244:245], v125 offset:20480
	ds_read_b64_tr_b16 v[246:247], v125 offset:20992
	ds_read_b64_tr_b16 v[248:249], v125 offset:24576
	ds_read_b64_tr_b16 v[250:251], v125 offset:25088
	ds_read_b64_tr_b16 v[158:159], v125 offset:28672
	ds_read_b64_tr_b16 v[160:161], v125 offset:29184
	ds_read_b64_tr_b16 v[166:167], v125 offset:17408
	ds_read_b64_tr_b16 v[168:169], v125 offset:17920
	s_waitcnt lgkmcnt(8)
	v_mfma_f32_32x32x16_bf16 v[50:65], v[216:219], v[240:243], v[50:65]
	ds_read_b64_tr_b16 v[240:241], v125 offset:21504
	ds_read_b64_tr_b16 v[242:243], v125 offset:22016
	v_exp_f32_e32 v82, v82
	v_exp_f32_e32 v83, v83
	v_exp_f32_e32 v84, v84
	v_exp_f32_e32 v85, v85
	s_waitcnt lgkmcnt(8)
	v_mfma_f32_32x32x16_bf16 v[34:49], v[216:219], v[244:247], v[34:49]
	ds_read_b64_tr_b16 v[244:245], v125 offset:25600
	ds_read_b64_tr_b16 v[246:247], v125 offset:26112
	v_add_f32_e32 v253, v82, v83
	v_exp_f32_e32 v86, v86
	v_exp_f32_e32 v87, v87
	v_add_f32_e32 v253, v253, v84
	s_waitcnt lgkmcnt(8)
	v_mfma_f32_32x32x16_bf16 v[18:33], v[216:219], v[248:251], v[18:33]
	ds_read_b64_tr_b16 v[248:249], v125 offset:29696
	ds_read_b64_tr_b16 v[250:251], v125 offset:30208
	v_add_f32_e32 v253, v253, v85
	v_exp_f32_e32 v88, v88
	v_exp_f32_e32 v89, v89
	v_add_f32_e32 v253, v253, v86
	v_add_f32_e32 v253, v253, v87
	s_waitcnt lgkmcnt(8)
	v_mfma_f32_32x32x16_bf16 v[2:17], v[216:219], v[158:161], v[2:17]
	ds_read_b64_tr_b16 v[158:159], v125 offset:18432
	ds_read_b64_tr_b16 v[160:161], v125 offset:18944
	v_exp_f32_e32 v90, v90
	v_exp_f32_e32 v91, v91
	v_add_f32_e32 v253, v253, v88
	v_add_f32_e32 v253, v253, v89
	v_cvt_pk_bf16_f32 v224, v82, v83
	s_waitcnt lgkmcnt(8)
	v_mfma_f32_32x32x16_bf16 v[50:65], v[220:223], v[166:169], v[50:65]
	ds_read_b64_tr_b16 v[166:167], v125 offset:22528
	ds_read_b64_tr_b16 v[168:169], v125 offset:23040
	v_cvt_pk_bf16_f32 v225, v84, v85
	v_cvt_pk_bf16_f32 v226, v86, v87
	v_cvt_pk_bf16_f32 v227, v88, v89
	v_exp_f32_e32 v92, v92
	v_exp_f32_e32 v93, v93
	s_waitcnt lgkmcnt(8)
	v_mfma_f32_32x32x16_bf16 v[34:49], v[220:223], v[240:243], v[34:49]
	ds_read_b64_tr_b16 v[240:241], v125 offset:26624
	ds_read_b64_tr_b16 v[242:243], v125 offset:27136
	v_add_f32_e32 v253, v253, v90
	v_add_f32_e32 v253, v253, v91
	v_exp_f32_e32 v94, v94
	v_exp_f32_e32 v95, v95
	v_add_f32_e32 v253, v253, v92
	s_waitcnt lgkmcnt(8)
	v_mfma_f32_32x32x16_bf16 v[18:33], v[220:223], v[244:247], v[18:33]
	ds_read_b64_tr_b16 v[244:245], v125 offset:30720
	ds_read_b64_tr_b16 v[246:247], v125 offset:31232
	v_add_f32_e32 v253, v253, v93
	v_exp_f32_e32 v96, v96
	v_exp_f32_e32 v97, v97
	v_add_f32_e32 v253, v253, v94
	v_add_f32_e32 v253, v253, v95
	s_waitcnt lgkmcnt(8)
	v_mfma_f32_32x32x16_bf16 v[2:17], v[220:223], v[248:251], v[2:17]
	ds_read_b64_tr_b16 v[248:249], v125 offset:19456
	ds_read_b64_tr_b16 v[250:251], v125 offset:19968
	v_add_f32_e32 v253, v253, v96
	v_add_f32_e32 v253, v253, v97
	v_cvt_pk_bf16_f32 v228, v90, v91
	v_cvt_pk_bf16_f32 v229, v92, v93
	v_cvt_pk_bf16_f32 v230, v94, v95
	v_cvt_pk_bf16_f32 v231, v96, v97
	v_add_f32_e32 v121, v121, v253
	s_waitcnt lgkmcnt(8)
	v_mfma_f32_32x32x16_bf16 v[50:65], v[224:227], v[158:161], v[50:65]
	ds_read_b64_tr_b16 v[158:159], v125 offset:23552
	ds_read_b64_tr_b16 v[160:161], v125 offset:24064
	s_waitcnt lgkmcnt(8)
	v_mfma_f32_32x32x16_bf16 v[34:49], v[224:227], v[166:169], v[34:49]
	ds_read_b64_tr_b16 v[166:167], v125 offset:27648
	ds_read_b64_tr_b16 v[168:169], v125 offset:28160
	s_waitcnt lgkmcnt(8)
	v_mfma_f32_32x32x16_bf16 v[18:33], v[224:227], v[240:243], v[18:33]
	ds_read_b64_tr_b16 v[240:241], v125 offset:31744
	ds_read_b64_tr_b16 v[242:243], v125 offset:32256
	s_waitcnt lgkmcnt(8)
	v_mfma_f32_32x32x16_bf16 v[2:17], v[224:227], v[244:247], v[2:17]
	s_waitcnt lgkmcnt(6)
	v_mfma_f32_32x32x16_bf16 v[50:65], v[228:231], v[248:251], v[50:65]
	s_waitcnt lgkmcnt(4)
	v_mfma_f32_32x32x16_bf16 v[34:49], v[228:231], v[158:161], v[34:49]
	s_waitcnt lgkmcnt(2)
	v_mfma_f32_32x32x16_bf16 v[18:33], v[228:231], v[166:169], v[18:33]
	s_waitcnt lgkmcnt(0)
	v_mfma_f32_32x32x16_bf16 v[2:17], v[228:231], v[240:243], v[2:17]
	s_waitcnt vmcnt(0)
	s_barrier
